# diff tile loops: the 8 MFMA->VALU wait states after QK filled with the next tile's K-fragment address adds (moved from loop top / post-barrier), V address and default alpha; loop top starts MFMAs righ
# speedup vs baseline: 1.0029x; 1.0029x over previous
.LBB0_132:
	s_and_b32 s5, s64, 7
	s_lshl_b32 s0, s5, 8
	s_or_b32 s22, s14, s0
	s_mov_b32 s23, s15
	s_lshl_b64 s[0:1], s[22:23], 10
	s_add_u32 s0, s55, s0
	s_addc_u32 s1, s56, s1
	s_lshl_b32 s4, s64, 4
	s_and_b32 s65, s4, 0x180
	s_lshl_b32 s4, s65, 1
	s_add_u32 s30, s0, s4
	s_addc_u32 s31, s1, 0
	s_lshl_b64 s[0:1], s[2:3], 21
	s_add_u32 s3, s57, s0
	s_addc_u32 s6, s58, s1
	s_add_u32 s24, s3, s4
	s_addc_u32 s25, s6, 0
	v_mov_b32_e32 v121, v218
	s_add_u32 s0, s90, s0
	v_mov_b32_e32 v4, v218
	s_addc_u32 s1, s91, s1
	s_add_u32 s3, s0, s4
	v_ashrrev_i32_e32 v0, 6, v4
	v_and_b32_e32 v6, 31, v4
	v_readfirstlane_b32 s0, v0
	v_lshl_or_b32 v0, v0, 5, v6
	v_ashrrev_i32_e32 v1, 31, v0
	v_lshlrev_b64 v[0:1], 10, v[0:1]
	v_lshrrev_b32_e32 v7, 1, v4
	v_and_b32_e32 v5, 63, v4
	v_lshl_add_u64 v[0:1], s[30:31], 0, v[0:1]
	v_and_b32_e32 v184, 16, v7
	s_addc_u32 s66, s1, 0
	v_lshl_add_u64 v[0:1], v[0:1], 0, v[184:185]
	s_lshl_b32 s1, s0, 10
	v_lshlrev_b32_e32 v8, 4, v5
	global_load_dwordx4 v[96:99], v[0:1], off
	global_load_dwordx4 v[100:103], v[0:1], off offset:32
	global_load_dwordx4 v[104:107], v[0:1], off offset:64
	global_load_dwordx4 v[108:111], v[0:1], off offset:96
	v_or_b32_e32 v0, s1, v8
	v_ashrrev_i32_e32 v1, 31, v0
	v_lshrrev_b32_e32 v1, 25, v1
	v_add_u32_e32 v1, v0, v1
	v_lshlrev_b32_e32 v9, 3, v5
	s_lshl_b32 s0, s0, 6
	v_ashrrev_i32_e32 v2, 7, v1
	v_and_b32_e32 v1, 0xffffff80, v1
	v_and_b32_e32 v3, 32, v4
	s_and_b32 s0, s0, 64
	v_and_b32_e32 v10, 24, v9
	v_sub_u32_e32 v0, v0, v1
	v_or3_b32 v3, v10, v3, s0
	s_ashr_i32 s0, s1, 8
	v_ashrrev_i32_e32 v0, 4, v0
	v_lshrrev_b32_e32 v1, 1, v2
	s_and_b32 s6, s0, 0x7ffff0
	s_lshr_b32 s0, s0, 1
	v_bitop3_b32 v0, v1, v0, 7 bitop3:0x6c
	v_bfe_u32 v1, v4, 2, 2
	s_and_b32 s0, s0, 4
	v_and_or_b32 v1, v7, 8, v1
	s_or_b32 s0, s6, s0
	v_or_b32_e32 v10, s0, v1
	s_add_i32 s0, s1, 0x2000
	s_ashr_i32 s0, s0, 8
	s_and_b32 s6, s0, 0x7ffff0
	s_lshr_b32 s0, s0, 1
	s_and_b32 s0, s0, 4
	s_or_b32 s0, s6, s0
	s_add_i32 s4, 0, 0x14000
	v_or_b32_e32 v1, s0, v1
	s_lshl_b32 s0, s5, 17
	s_lshl_b32 s6, s5, 18
	v_lshl_or_b32 v114, v1, 9, v3
	v_lshlrev_b32_e32 v1, 9, v2
	s_add_u32 s68, s24, s6
	v_lshl_add_u32 v0, v0, 3, v1
	s_addc_u32 s69, s25, 0
	s_add_i32 s5, s1, 0
	v_ashrrev_i32_e32 v1, 31, v0
	s_add_i32 m0, s5, 0x8000
	v_lshl_or_b32 v112, v10, 9, v3
	v_lshlrev_b64 v[0:1], 1, v[0:1]
	s_add_u32 s34, s3, s6
	v_lshl_add_u64 v[2:3], s[68:69], 0, v[0:1]
	s_addc_u32 s35, s66, 0
	v_ashrrev_i32_e32 v113, 31, v112
	s_waitcnt lgkmcnt(0)
	global_load_lds_dwordx4 v[2:3], off
	v_lshl_add_u64 v[2:3], v[112:113], 1, s[34:35]
	s_mov_b32 m0, s5
	v_ashrrev_i32_e32 v115, 31, v114
	global_load_lds_dwordx4 v[2:3], off
	v_lshl_add_u64 v[2:3], v[114:115], 1, s[34:35]
	s_add_i32 m0, s5, 0x2000
	s_cmp_lg_u32 0, -1
	global_load_lds_dwordx4 v[2:3], off
	v_and_b32_e32 v2, 0x3fffffc0, v4
	v_lshl_add_u32 v119, v2, 2, s4
	v_lshlrev_b32_e32 v2, 1, v4
	s_cselect_b32 s1, 0, 0
	v_and_b32_e32 v2, 32, v2
	v_lshlrev_b32_e32 v4, 3, v4
	s_add_i32 s6, s1, 0x8000
	s_movk_i32 s54, 0x118
	v_and_b32_e32 v3, 0xc0, v8
	v_and_b32_e32 v4, 0x70, v4
	v_lshl_add_u32 v120, v6, 7, s6
	s_movk_i32 s6, 0x60
	v_lshl_add_u64 v[116:117], s[24:25], 0, v[0:1]
	v_mov_b32_e32 v194, v0
	v_lshlrev_b32_e32 v195, 1, v112
	v_lshlrev_b32_e32 v196, 1, v114
	v_and_or_b32 v0, v9, s54, v2
	v_mov_b32_e32 v14, v185
	v_mov_b32_e32 v15, v185
	v_bitop3_b32 v123, v7, v4, 16 bitop3:0x6c
	v_bitop3_b32 v124, v184, v4, 32 bitop3:0x36
	v_bitop3_b32 v125, v184, v4, 64 bitop3:0x36
	v_bitop3_b32 v126, v184, v4, s6 bitop3:0x36
	v_cmp_gt_u32_e64 s[6:7], 32, v5
	v_lshl_add_u32 v122, v6, 2, v119
	v_add3_u32 v127, v3, s1, v0
	s_or_b32 s67, s0, 0x8000
	v_mov_b32_e32 v0, v185
	v_mov_b32_e32 v1, v185
	v_mov_b32_e32 v2, v185
	v_mov_b32_e32 v3, v185
	v_mov_b32_e32 v4, v185
	v_mov_b32_e32 v5, v185
	v_mov_b32_e32 v6, v185
	v_mov_b32_e32 v7, v185
	v_mov_b32_e32 v8, v185
	v_mov_b32_e32 v9, v185
	v_mov_b32_e32 v10, v185
	v_mov_b32_e32 v11, v185
	v_mov_b32_e32 v12, v185
	v_mov_b32_e32 v13, v185
	v_mov_b64_e32 v[30:31], v[14:15]
	v_mov_b64_e32 v[46:47], v[14:15]
	v_mov_b64_e32 v[62:63], v[14:15]
	s_mov_b32 s53, 0
	v_mov_b32_e32 v128, 0
	v_mov_b32_e32 v160, 0x80000000
	v_mov_b32_e32 v161, 0x80000000
	v_mov_b32_e32 v162, 0x80000000
	v_mov_b32_e32 v163, 0x80000000
	v_mov_b32_e32 v164, 0x80000000
	v_mov_b32_e32 v165, 0x80000000
	v_mov_b32_e32 v166, 0x80000000
	v_mov_b32_e32 v167, 0x80000000
	v_mov_b32_e32 v168, 0x80000000
	v_mov_b32_e32 v169, 0x80000000
	v_mov_b32_e32 v170, 0x80000000
	v_mov_b32_e32 v171, 0x80000000
	v_mov_b32_e32 v172, 0x80000000
	v_mov_b32_e32 v173, 0x80000000
	v_mov_b32_e32 v174, 0x80000000
	v_mov_b32_e32 v175, 0x80000000
	s_mov_b32 s54, s67
	v_mov_b64_e32 v[28:29], v[12:13]
	v_mov_b64_e32 v[26:27], v[10:11]
	v_mov_b64_e32 v[24:25], v[8:9]
	v_mov_b64_e32 v[22:23], v[6:7]
	v_mov_b64_e32 v[20:21], v[4:5]
	v_mov_b64_e32 v[18:19], v[2:3]
	v_mov_b64_e32 v[16:17], v[0:1]
	v_mov_b64_e32 v[44:45], v[12:13]
	v_mov_b64_e32 v[42:43], v[10:11]
	v_mov_b64_e32 v[40:41], v[8:9]
	v_mov_b64_e32 v[38:39], v[6:7]
	v_mov_b64_e32 v[36:37], v[4:5]
	v_mov_b64_e32 v[34:35], v[2:3]
	v_mov_b64_e32 v[32:33], v[0:1]
	v_mov_b64_e32 v[60:61], v[12:13]
	v_mov_b64_e32 v[58:59], v[10:11]
	v_mov_b64_e32 v[56:57], v[8:9]
	v_mov_b64_e32 v[54:55], v[6:7]
	v_mov_b64_e32 v[52:53], v[4:5]
	v_mov_b64_e32 v[50:51], v[2:3]
	v_mov_b64_e32 v[48:49], v[0:1]
	v_mov_b32_e32 v129, 0
	s_waitcnt vmcnt(0) lgkmcnt(0)
	s_barrier
	s_and_b32 s80, s53, 1
	v_add_u32_e32 v217, v120, v123
	ds_read_b128 v[130:133], v217 offset:0
	ds_read_b128 v[134:137], v217 offset:0x1000
	v_add_u32_e32 v210, v120, v124
	v_add_u32_e32 v211, v120, v125
	v_add_u32_e32 v197, v120, v126
	ds_read_b128 v[202:205], v210 offset:0
	ds_read_b128 v[206:209], v210 offset:0x1000
	s_cmp_eq_u32 s53, 31
	s_movk_i32 s0, 0x2000
	s_cbranch_scc1 .LBB0_134

.LBB0_134:
	s_waitcnt lgkmcnt(2)
	v_mfma_f32_32x32x16_bf16 v[80:95], v[130:133], v[96:99], v[160:175]
	ds_read_b128 v[130:133], v211 offset:0
	v_mfma_f32_32x32x16_bf16 v[64:79], v[134:137], v[96:99], v[160:175]
	ds_read_b128 v[134:137], v211 offset:0x1000
	s_waitcnt lgkmcnt(2)
	v_mfma_f32_32x32x16_bf16 v[80:95], v[202:205], v[100:103], v[80:95]
	ds_read_b128 v[138:141], v197 offset:0
	v_mfma_f32_32x32x16_bf16 v[64:79], v[206:209], v[100:103], v[64:79]
	ds_read_b128 v[146:149], v197 offset:0x1000
	s_waitcnt lgkmcnt(2)
	v_mfma_f32_32x32x16_bf16 v[80:95], v[130:133], v[104:107], v[80:95]
	s_waitcnt lgkmcnt(0)
	v_mfma_f32_32x32x16_bf16 v[64:79], v[134:137], v[104:107], v[64:79]
	v_mfma_f32_32x32x16_bf16 v[80:95], v[138:141], v[108:111], v[80:95]
	s_xor_b32 s1, s80, 1
	s_lshl_b32 s1, s1, 13
	s_cmp_eq_u32 s53, 0
	s_cselect_b64 s[70:71], -1, 0
	s_cmp_lg_u32 s53, 0
	v_mfma_f32_32x32x16_bf16 v[64:79], v[146:149], v[108:111], v[64:79]
	v_add3_u32 v217, v120, v123, s1
	v_add3_u32 v210, v120, v124, s1
	v_add3_u32 v211, v120, v125, s1
	v_add3_u32 v197, v120, v126, s1
	v_lshl_add_u32 v199, s80, 14, v127
	v_mov_b32_e32 v130, 1.0
	s_nop 1
	v_max_f32_e32 v118, v80, v81
	v_max3_f32 v118, v118, v82, v83
	v_max3_f32 v118, v118, v84, v85
	v_max3_f32 v118, v118, v86, v87
	v_max3_f32 v118, v118, v88, v89
	v_max3_f32 v118, v118, v90, v91
	v_max3_f32 v118, v118, v92, v93
	v_max3_f32 v118, v118, v94, v95
	v_max3_f32 v118, v118, v64, v65
	v_max3_f32 v118, v118, v66, v67
	v_max3_f32 v118, v118, v68, v69
	v_max3_f32 v118, v118, v70, v71
	v_max3_f32 v118, v118, v72, v73
	v_max3_f32 v118, v118, v74, v75
	v_max3_f32 v118, v118, v76, v77
	v_max3_f32 v118, v118, v78, v79
	s_cbranch_scc0 .Lmx1_first
	v_cmp_ge_f32_e32 vcc, s62, v118
	s_cmp_lg_u64 vcc, exec
	s_mov_b64 s[74:75], 0
	s_mov_b64 s[72:73], 0
	s_cbranch_scc1 .Lmx1_slow
	s_branch .LBB0_146

.LBB0_146:
	v_exp_f32_e32 v80, v80
	v_exp_f32_e32 v81, v81
	v_exp_f32_e32 v82, v82
	v_exp_f32_e32 v83, v83
	v_exp_f32_e32 v84, v84
	v_exp_f32_e32 v118, v64
	v_exp_f32_e32 v85, v85
	v_add_f32_e32 v64, v81, v80
	v_exp_f32_e32 v86, v86
	v_add_f32_e32 v64, v82, v64
	v_exp_f32_e32 v87, v87
	v_add_f32_e32 v64, v83, v64
	v_exp_f32_e32 v88, v88
	v_add_f32_e32 v64, v84, v64
	v_exp_f32_e32 v89, v89
	v_add_f32_e32 v64, v85, v64
	v_exp_f32_e32 v90, v90
	v_add_f32_e32 v64, v86, v64
	v_exp_f32_e32 v91, v91
	v_add_f32_e32 v64, v87, v64
	v_exp_f32_e32 v92, v92
	v_add_f32_e32 v64, v88, v64
	v_exp_f32_e32 v93, v93
	v_add_f32_e32 v64, v89, v64
	v_exp_f32_e32 v94, v94
	v_add_f32_e32 v64, v90, v64
	v_exp_f32_e32 v95, v95
	v_add_f32_e32 v64, v91, v64
	v_add_f32_e32 v64, v92, v64
	v_exp_f32_e32 v65, v65
	v_add_f32_e32 v64, v93, v64
	v_exp_f32_e32 v131, v66
	v_add_f32_e32 v64, v94, v64
	v_exp_f32_e32 v132, v67
	v_add_f32_e32 v64, v95, v64
	v_exp_f32_e32 v133, v68
	v_add_f32_e32 v64, v118, v64
	v_exp_f32_e32 v134, v69
	v_add_f32_e32 v64, v65, v64
	v_exp_f32_e32 v135, v70
	v_add_f32_e32 v64, v131, v64
	v_exp_f32_e32 v136, v71
	v_add_f32_e32 v64, v132, v64
	v_exp_f32_e32 v137, v72
	v_add_f32_e32 v64, v133, v64
	v_exp_f32_e32 v138, v73
	v_add_f32_e32 v64, v134, v64
	v_exp_f32_e32 v139, v74
	v_add_f32_e32 v64, v135, v64
	v_exp_f32_e32 v140, v75
	v_add_f32_e32 v64, v136, v64
	v_exp_f32_e32 v141, v76
	v_add_f32_e32 v64, v137, v64
	v_exp_f32_e32 v142, v77
	v_add_f32_e32 v64, v138, v64
	v_exp_f32_e32 v143, v78
	v_add_f32_e32 v64, v139, v64
	v_exp_f32_e32 v146, v79
	v_add_f32_e32 v64, v140, v64
	v_add_f32_e32 v64, v141, v64
	v_add_f32_e32 v64, v142, v64
	v_add_f32_e32 v64, v143, v64
	v_add_f32_e32 v64, v146, v64
	s_add_i32 s53, s53, 1
	v_fma_f32 v129, v129, v130, v64
	v_cvt_pk_bf16_f32 v66, v80, v81
	v_cvt_pk_bf16_f32 v67, v82, v83
	v_cvt_pk_bf16_f32 v68, v84, v85
	v_cvt_pk_bf16_f32 v69, v86, v87
	v_cvt_pk_bf16_f32 v70, v88, v89
	v_cvt_pk_bf16_f32 v71, v90, v91
	v_cvt_pk_bf16_f32 v72, v92, v93
	v_cvt_pk_bf16_f32 v73, v94, v95
	v_cvt_pk_bf16_f32 v74, v118, v65
	v_cvt_pk_bf16_f32 v75, v131, v132
	v_cvt_pk_bf16_f32 v76, v133, v134
	v_cvt_pk_bf16_f32 v77, v135, v136
	v_cvt_pk_bf16_f32 v78, v137, v138
	v_cvt_pk_bf16_f32 v79, v139, v140
	v_cvt_pk_bf16_f32 v80, v141, v142
	v_cvt_pk_bf16_f32 v81, v143, v146
	s_nop 0
	v_permlane32_swap_b32_e32 v66, v68
	v_permlane32_swap_b32_e32 v67, v69
	v_permlane32_swap_b32_e32 v70, v72
	v_permlane32_swap_b32_e32 v71, v73
	v_permlane32_swap_b32_e32 v74, v76
	v_permlane32_swap_b32_e32 v75, v77
	v_permlane32_swap_b32_e32 v78, v80
	v_permlane32_swap_b32_e32 v79, v81
	ds_read_b64_tr_b16 v[82:83], v199 offset:0
	ds_read_b64_tr_b16 v[84:85], v199 offset:0x800
	ds_read_b64_tr_b16 v[86:87], v199 offset:0x1000
	ds_read_b64_tr_b16 v[88:89], v199 offset:0x1800
	ds_read_b64_tr_b16 v[90:91], v199 offset:0x2000
	ds_read_b64_tr_b16 v[92:93], v199 offset:0x2800
	ds_read_b64_tr_b16 v[130:131], v199 offset:0x3000
	ds_read_b64_tr_b16 v[132:133], v199 offset:0x3800
	ds_read_b64_tr_b16 v[134:135], v199 offset:0x200
	ds_read_b64_tr_b16 v[136:137], v199 offset:0xa00
	ds_read_b64_tr_b16 v[138:139], v199 offset:0x1200
	ds_read_b64_tr_b16 v[140:141], v199 offset:0x1a00
	ds_read_b64_tr_b16 v[146:147], v199 offset:0x2200
	ds_read_b64_tr_b16 v[148:149], v199 offset:0x2a00
	ds_read_b64_tr_b16 v[150:151], v199 offset:0x3200
	ds_read_b64_tr_b16 v[152:153], v199 offset:0x3a00
	s_waitcnt lgkmcnt(8)
	s_nop 0
	v_mfma_f32_32x32x16_bf16 v[48:63], v[66:69], v[82:85], v[48:63]
	ds_read_b64_tr_b16 v[82:83], v199 offset:0x400
	ds_read_b64_tr_b16 v[84:85], v199 offset:0xc00
	v_mfma_f32_32x32x16_bf16 v[48:63], v[70:73], v[86:89], v[48:63]
	ds_read_b64_tr_b16 v[86:87], v199 offset:0x1400
	ds_read_b64_tr_b16 v[88:89], v199 offset:0x1c00
	v_mfma_f32_32x32x16_bf16 v[48:63], v[74:77], v[90:93], v[48:63]
	ds_read_b64_tr_b16 v[90:91], v199 offset:0x2400
	ds_read_b64_tr_b16 v[92:93], v199 offset:0x2c00
	v_mfma_f32_32x32x16_bf16 v[48:63], v[78:81], v[130:133], v[48:63]
	ds_read_b64_tr_b16 v[130:131], v199 offset:0x3400
	ds_read_b64_tr_b16 v[132:133], v199 offset:0x3c00
	s_waitcnt lgkmcnt(8)
	v_mfma_f32_32x32x16_bf16 v[32:47], v[66:69], v[134:137], v[32:47]
	ds_read_b64_tr_b16 v[134:135], v199 offset:0x600
	ds_read_b64_tr_b16 v[136:137], v199 offset:0xe00
	v_mfma_f32_32x32x16_bf16 v[32:47], v[70:73], v[138:141], v[32:47]
	ds_read_b64_tr_b16 v[138:139], v199 offset:0x1600
	ds_read_b64_tr_b16 v[140:141], v199 offset:0x1e00
	v_mfma_f32_32x32x16_bf16 v[32:47], v[74:77], v[146:149], v[32:47]
	ds_read_b64_tr_b16 v[146:147], v199 offset:0x2600
	ds_read_b64_tr_b16 v[148:149], v199 offset:0x2e00
	v_mfma_f32_32x32x16_bf16 v[32:47], v[78:81], v[150:153], v[32:47]
	ds_read_b64_tr_b16 v[150:151], v199 offset:0x3600
	ds_read_b64_tr_b16 v[152:153], v199 offset:0x3e00
	s_waitcnt lgkmcnt(8)
	v_mfma_f32_32x32x16_bf16 v[16:31], v[66:69], v[82:85], v[16:31]
	s_waitcnt lgkmcnt(0)
	v_mfma_f32_32x32x16_bf16 v[16:31], v[70:73], v[86:89], v[16:31]
	v_mfma_f32_32x32x16_bf16 v[16:31], v[74:77], v[90:93], v[16:31]
	v_mfma_f32_32x32x16_bf16 v[16:31], v[78:81], v[130:133], v[16:31]
	v_mfma_f32_32x32x16_bf16 v[0:15], v[66:69], v[134:137], v[0:15]
	s_waitcnt vmcnt(0)
	s_add_i32 s54, s54, 0x8000
	s_cmp_eq_u32 s53, 32
	s_waitcnt vmcnt(0) lgkmcnt(0)
	s_barrier
	ds_read_b128 v[130:133], v217 offset:0
	ds_read_b128 v[134:137], v217 offset:0x1000
	ds_read_b128 v[202:205], v210 offset:0
	ds_read_b128 v[206:209], v210 offset:0x1000
	s_cmp_eq_u32 s53, 32
	v_mfma_f32_32x32x16_bf16 v[0:15], v[70:73], v[138:141], v[0:15]
	v_mfma_f32_32x32x16_bf16 v[0:15], v[74:77], v[146:149], v[0:15]
	v_mfma_f32_32x32x16_bf16 v[0:15], v[78:81], v[150:153], v[0:15]
	s_cbranch_scc1 .LBB0_148
	s_and_b32 s80, s53, 1
	s_cmp_eq_u32 s53, 31
	s_movk_i32 s0, 0x2000
	s_cbranch_scc0 .LBB0_133
	s_branch .LBB0_134
.LBB0_148:
	v_ashrrev_i32_e32 v194, 6, v218
	v_and_b32_e32 v196, 31, v218
	v_lshl_or_b32 v194, v194, 5, v196
	v_ashrrev_i32_e32 v195, 31, v194
	v_lshlrev_b64 v[194:195], 10, v[194:195]
	v_lshl_add_u64 v[194:195], s[30:31], 0, v[194:195]
	v_lshl_add_u64 v[194:195], v[194:195], 0, v[184:185]
	global_load_dwordx4 v[96:99], v[194:195], off offset:128
	global_load_dwordx4 v[100:103], v[194:195], off offset:160
	global_load_dwordx4 v[104:107], v[194:195], off offset:192
	global_load_dwordx4 v[108:111], v[194:195], off offset:224
	s_sub_u32 s0, s68, s24
	s_subb_u32 s1, s69, s25
	s_add_u32 s0, s0, s78
	s_addc_u32 s1, s1, s79
	s_add_i32 m0, s5, 0x8000
	v_lshl_add_u64 v[198:199], v[116:117], 0, s[0:1]
	global_load_lds_dwordx4 v[198:199], off
	v_lshl_add_u64 v[198:199], v[112:113], 1, s[34:35]
	s_mov_b32 m0, s5
	s_nop 0
	global_load_lds_dwordx4 v[198:199], off
	v_lshl_add_u64 v[198:199], v[114:115], 1, s[34:35]
	s_add_i32 m0, s5, 0x2000
	s_nop 0
	global_load_lds_dwordx4 v[198:199], off
	v_mov_b32_e32 v66, v129
	s_nop 1
	v_permlane32_swap_b32_e32 v129, v66
	v_add_f32_e32 v64, v129, v66
	s_and_saveexec_b64 s[0:1], s[6:7]
	ds_write_b32 v122, v64
	s_or_b64 exec, exec, s[0:1]
	v_lshlrev_b32_e32 v64, 6, v121
	v_ashrrev_i32_e32 v65, 31, v64
	s_waitcnt lgkmcnt(0)
	v_add_u32_e32 v80, v119, v184
	v_lshl_add_u64 v[112:113], v[64:65], 2, s[12:13]
	ds_read_b128 v[64:67], v80
	ds_read_b128 v[68:71], v80 offset:32
	s_mov_b32 s5, 0
	v_mov_b32_e32 v130, 0
	v_mov_b32_e32 v131, 0
	s_waitcnt lgkmcnt(1)
	v_rcp_f32_e32 v72, v64
	v_rcp_f32_e32 v73, v65
	v_rcp_f32_e32 v74, v66
	v_rcp_f32_e32 v75, v67
	ds_read_b128 v[64:67], v80 offset:64
	s_waitcnt lgkmcnt(1)
	v_rcp_f32_e32 v68, v68
	v_rcp_f32_e32 v69, v69
	v_rcp_f32_e32 v70, v70
	v_rcp_f32_e32 v71, v71
	s_waitcnt lgkmcnt(0)
	v_rcp_f32_e32 v76, v64
	v_rcp_f32_e32 v77, v65
	v_rcp_f32_e32 v78, v66
	v_rcp_f32_e32 v79, v67
	ds_read_b128 v[64:67], v80 offset:96
	v_pk_mul_f32 v[48:49], v[48:49], v[72:73]
	v_pk_mul_f32 v[50:51], v[50:51], v[74:75]
	v_pk_mul_f32 v[32:33], v[32:33], v[72:73]
	v_pk_mul_f32 v[34:35], v[34:35], v[74:75]
	s_waitcnt lgkmcnt(0)
	v_rcp_f32_e32 v64, v64
	v_rcp_f32_e32 v65, v65
	v_rcp_f32_e32 v66, v66
	v_rcp_f32_e32 v67, v67
	v_pk_mul_f32 v[16:17], v[16:17], v[72:73]
	v_pk_mul_f32 v[18:19], v[18:19], v[74:75]
	v_pk_mul_f32 v[0:1], v[0:1], v[72:73]
	v_pk_mul_f32 v[2:3], v[2:3], v[74:75]
	global_store_dwordx4 v[112:113], v[48:51], off
	global_store_dwordx4 v[112:113], v[32:35], off offset:64
	global_store_dwordx4 v[112:113], v[16:19], off offset:128
	v_pk_mul_f32 v[48:49], v[52:53], v[68:69]
	v_pk_mul_f32 v[50:51], v[54:55], v[70:71]
	v_pk_mul_f32 v[32:33], v[36:37], v[68:69]
	v_pk_mul_f32 v[34:35], v[38:39], v[70:71]
	v_pk_mul_f32 v[16:17], v[20:21], v[68:69]
	v_pk_mul_f32 v[18:19], v[22:23], v[70:71]
	global_store_dwordx4 v[112:113], v[0:3], off offset:192
	global_store_dwordx4 v[112:113], v[48:51], off offset:16
	global_store_dwordx4 v[112:113], v[32:35], off offset:80
	v_pk_mul_f32 v[0:1], v[4:5], v[68:69]
	v_pk_mul_f32 v[2:3], v[6:7], v[70:71]
	v_pk_mul_f32 v[48:49], v[56:57], v[76:77]
	v_pk_mul_f32 v[50:51], v[58:59], v[78:79]
	v_pk_mul_f32 v[32:33], v[40:41], v[76:77]
	v_pk_mul_f32 v[34:35], v[42:43], v[78:79]
	global_store_dwordx4 v[112:113], v[16:19], off offset:144
	global_store_dwordx4 v[112:113], v[0:3], off offset:208
	global_store_dwordx4 v[112:113], v[48:51], off offset:32
	v_pk_mul_f32 v[16:17], v[24:25], v[76:77]
	v_pk_mul_f32 v[18:19], v[26:27], v[78:79]
	v_pk_mul_f32 v[0:1], v[8:9], v[76:77]
	v_pk_mul_f32 v[2:3], v[10:11], v[78:79]
	v_pk_mul_f32 v[48:49], v[60:61], v[64:65]
	v_pk_mul_f32 v[50:51], v[62:63], v[66:67]
	global_store_dwordx4 v[112:113], v[32:35], off offset:96
	global_store_dwordx4 v[112:113], v[16:19], off offset:160
	global_store_dwordx4 v[112:113], v[0:3], off offset:224
	v_pk_mul_f32 v[32:33], v[44:45], v[64:65]
	v_pk_mul_f32 v[34:35], v[46:47], v[66:67]
	v_pk_mul_f32 v[16:17], v[28:29], v[64:65]
	v_pk_mul_f32 v[18:19], v[30:31], v[66:67]
	v_pk_mul_f32 v[0:1], v[12:13], v[64:65]
	v_pk_mul_f32 v[2:3], v[14:15], v[66:67]
	v_mov_b32_e32 v4, v218
	global_store_dwordx4 v[112:113], v[48:51], off offset:48
	global_store_dwordx4 v[112:113], v[32:35], off offset:112
	global_store_dwordx4 v[112:113], v[16:19], off offset:176
	global_store_dwordx4 v[112:113], v[0:3], off offset:240
	v_mov_b32_e32 v14, v185
	v_and_b32_e32 v6, 31, v4
	v_and_b32_e32 v0, 0x3fffffc0, v4
	v_lshl_add_u32 v122, v0, 2, s4
	v_ashrrev_i32_e32 v0, 6, v4
	v_lshrrev_b32_e32 v7, 1, v4
	v_readfirstlane_b32 s0, v0
	v_lshl_or_b32 v0, v0, 5, v6
	v_ashrrev_i32_e32 v1, 31, v0
	v_lshlrev_b64 v[0:1], 10, v[0:1]
	v_and_b32_e32 v5, 63, v4
	v_lshl_add_u64 v[0:1], s[30:31], 0, v[0:1]
	v_and_b32_e32 v184, 16, v7
	v_lshl_add_u64 v[0:1], v[0:1], 0, v[184:185]
	s_lshl_b32 s1, s0, 10
	v_lshlrev_b32_e32 v8, 4, v5
	v_or_b32_e32 v0, s1, v8
	v_ashrrev_i32_e32 v1, 31, v0
	v_lshrrev_b32_e32 v1, 25, v1
	v_add_u32_e32 v1, v0, v1
	v_lshlrev_b32_e32 v9, 3, v5
	s_lshl_b32 s0, s0, 6
	v_ashrrev_i32_e32 v2, 7, v1
	v_and_b32_e32 v1, 0xffffff80, v1
	v_and_b32_e32 v3, 32, v4
	s_and_b32 s0, s0, 64
	v_and_b32_e32 v10, 24, v9
	v_sub_u32_e32 v0, v0, v1
	v_or3_b32 v3, v10, v3, s0
	s_ashr_i32 s0, s1, 8
	v_ashrrev_i32_e32 v0, 4, v0
	v_lshrrev_b32_e32 v1, 1, v2
	s_and_b32 s4, s0, 0x7ffff0
	s_lshr_b32 s0, s0, 1
	v_bitop3_b32 v0, v1, v0, 7 bitop3:0x6c
	v_bfe_u32 v1, v4, 2, 2
	s_and_b32 s0, s0, 4
	v_and_or_b32 v1, v7, 8, v1
	s_or_b32 s0, s4, s0
	v_or_b32_e32 v10, s0, v1
	s_add_i32 s0, s1, 0x2000
	s_ashr_i32 s0, s0, 8
	s_and_b32 s4, s0, 0x7ffff0
	s_lshr_b32 s0, s0, 1
	s_and_b32 s0, s0, 4
	s_or_b32 s0, s4, s0
	v_or_b32_e32 v1, s0, v1
	v_lshl_or_b32 v116, v1, 9, v3
	v_lshlrev_b32_e32 v1, 9, v2
	v_lshl_add_u32 v0, v0, 3, v1
	v_ashrrev_i32_e32 v1, 31, v0
	v_lshlrev_b64 v[0:1], 1, v[0:1]
	v_lshl_or_b32 v114, v10, 9, v3
	v_lshl_add_u64 v[2:3], s[68:69], 0, v[0:1]
	s_add_i32 s4, s1, 0
	v_lshl_add_u64 v[2:3], v[2:3], 0, s[78:79]
	s_add_i32 m0, s4, 0x8000
	v_ashrrev_i32_e32 v115, 31, v114
	v_lshl_add_u64 v[2:3], v[114:115], 1, s[34:35]
	s_mov_b32 m0, s4
	v_ashrrev_i32_e32 v117, 31, v116
	v_lshl_add_u64 v[2:3], v[116:117], 1, s[34:35]
	s_add_i32 m0, s4, 0x2000
	s_cmp_lg_u32 0, -1
	s_cselect_b32 s0, 0, 0
	v_lshlrev_b32_e32 v10, 1, v4
	v_lshlrev_b32_e32 v4, 3, v4
	s_add_i32 s1, s0, 0x8000
	v_and_b32_e32 v4, 0x70, v4
	v_lshl_add_u32 v124, v6, 7, s1
	s_movk_i32 s1, 0x60
	v_and_b32_e32 v3, 32, v10
	v_bitop3_b32 v128, v184, v4, s1 bitop3:0x36
	s_movk_i32 s1, 0x118
	v_and_b32_e32 v2, 0xc0, v8
	v_lshl_add_u64 v[118:119], s[24:25], 0, v[0:1]
	v_mov_b32_e32 v194, v0
	v_lshlrev_b32_e32 v195, 1, v114
	v_lshlrev_b32_e32 v196, 1, v116
	s_add_u32 s100, s24, 0x80
	s_addc_u32 s101, s25, 0
	v_and_or_b32 v0, v9, s1, v3
	v_mov_b32_e32 v15, v185
	v_bitop3_b32 v125, v7, v4, 16 bitop3:0x6c
	v_bitop3_b32 v126, v184, v4, 32 bitop3:0x36
	v_bitop3_b32 v127, v184, v4, 64 bitop3:0x36
	v_cmp_gt_u32_e64 s[6:7], 32, v5
	v_lshl_add_u32 v123, v6, 2, v122
	v_add3_u32 v129, v2, s0, v0
	v_mov_b32_e32 v0, v185
	v_mov_b32_e32 v1, v185
	v_mov_b32_e32 v2, v185
	v_mov_b32_e32 v3, v185
	v_mov_b32_e32 v4, v185
	v_mov_b32_e32 v5, v185
	v_mov_b32_e32 v6, v185
	v_mov_b32_e32 v7, v185
	v_mov_b32_e32 v8, v185
	v_mov_b32_e32 v9, v185
	v_mov_b32_e32 v10, v185
	v_mov_b32_e32 v11, v185
	v_mov_b32_e32 v12, v185
	v_mov_b32_e32 v13, v185
	v_mov_b64_e32 v[30:31], v[14:15]
	v_mov_b64_e32 v[46:47], v[14:15]
	v_mov_b64_e32 v[62:63], v[14:15]
	v_mov_b64_e32 v[28:29], v[12:13]
	v_mov_b64_e32 v[26:27], v[10:11]
	v_mov_b64_e32 v[24:25], v[8:9]
	v_mov_b64_e32 v[22:23], v[6:7]
	v_mov_b64_e32 v[20:21], v[4:5]
	v_mov_b64_e32 v[18:19], v[2:3]
	v_mov_b64_e32 v[16:17], v[0:1]
	v_mov_b64_e32 v[44:45], v[12:13]
	v_mov_b64_e32 v[42:43], v[10:11]
	v_mov_b64_e32 v[40:41], v[8:9]
	v_mov_b64_e32 v[38:39], v[6:7]
	v_mov_b64_e32 v[36:37], v[4:5]
	v_mov_b64_e32 v[34:35], v[2:3]
	v_mov_b64_e32 v[32:33], v[0:1]
	v_mov_b64_e32 v[60:61], v[12:13]
	v_mov_b64_e32 v[58:59], v[10:11]
	v_mov_b64_e32 v[56:57], v[8:9]
	v_mov_b64_e32 v[54:55], v[6:7]
	v_mov_b64_e32 v[52:53], v[4:5]
	v_mov_b64_e32 v[50:51], v[2:3]
	v_mov_b64_e32 v[48:49], v[0:1]
	v_mov_b32_e32 v160, 0x80000000
	v_mov_b32_e32 v161, 0x80000000
	v_mov_b32_e32 v162, 0x80000000
	v_mov_b32_e32 v163, 0x80000000
	v_mov_b32_e32 v164, 0x80000000
	v_mov_b32_e32 v165, 0x80000000
	v_mov_b32_e32 v166, 0x80000000
	v_mov_b32_e32 v167, 0x80000000
	v_mov_b32_e32 v168, 0x80000000
	v_mov_b32_e32 v169, 0x80000000
	v_mov_b32_e32 v170, 0x80000000
	v_mov_b32_e32 v171, 0x80000000
	v_mov_b32_e32 v172, 0x80000000
	v_mov_b32_e32 v173, 0x80000000
	v_mov_b32_e32 v174, 0x80000000
	v_mov_b32_e32 v175, 0x80000000
	v_readlane_b32 s54, v254, 48
	s_waitcnt vmcnt(16) lgkmcnt(0)
	s_barrier
	s_and_b32 s53, s5, 1
	v_add_u32_e32 v217, v124, v125
	ds_read_b128 v[132:135], v217 offset:0
	ds_read_b128 v[136:139], v217 offset:0x1000
	v_add_u32_e32 v210, v124, v126
	v_add_u32_e32 v211, v124, v127
	v_add_u32_e32 v197, v124, v128
	ds_read_b128 v[202:205], v210 offset:0
	ds_read_b128 v[206:209], v210 offset:0x1000
	s_cmp_eq_u32 s5, 31
	s_movk_i32 s0, 0x2000
	s_cbranch_scc1 .LBB0_152

.LBB0_152:
	s_waitcnt lgkmcnt(2)
	v_mfma_f32_32x32x16_bf16 v[80:95], v[132:135], v[96:99], v[160:175]
	ds_read_b128 v[132:135], v211 offset:0
	v_mfma_f32_32x32x16_bf16 v[64:79], v[136:139], v[96:99], v[160:175]
	ds_read_b128 v[136:139], v211 offset:0x1000
	s_waitcnt lgkmcnt(2)
	v_mfma_f32_32x32x16_bf16 v[80:95], v[202:205], v[100:103], v[80:95]
	ds_read_b128 v[140:143], v197 offset:0
	v_mfma_f32_32x32x16_bf16 v[64:79], v[206:209], v[100:103], v[64:79]
	ds_read_b128 v[146:149], v197 offset:0x1000
	s_waitcnt lgkmcnt(2)
	v_mfma_f32_32x32x16_bf16 v[80:95], v[132:135], v[104:107], v[80:95]
	s_waitcnt lgkmcnt(0)
	v_mfma_f32_32x32x16_bf16 v[64:79], v[136:139], v[104:107], v[64:79]
	v_mfma_f32_32x32x16_bf16 v[80:95], v[140:143], v[108:111], v[80:95]
	s_xor_b32 s1, s53, 1
	s_lshl_b32 s1, s1, 13
	s_cmp_eq_u32 s5, 0
	s_cselect_b64 s[24:25], -1, 0
	s_cmp_lg_u32 s5, 0
	v_mfma_f32_32x32x16_bf16 v[64:79], v[146:149], v[108:111], v[64:79]
	v_add3_u32 v217, v124, v125, s1
	v_add3_u32 v210, v124, v126, s1
	v_add3_u32 v211, v124, v127, s1
	v_add3_u32 v197, v124, v128, s1
	v_lshl_add_u32 v199, s53, 14, v129
	v_mov_b32_e32 v132, 1.0
	s_nop 1
	v_max_f32_e32 v120, v80, v81
	v_max3_f32 v120, v120, v82, v83
	v_max3_f32 v120, v120, v84, v85
	v_max3_f32 v120, v120, v86, v87
	v_max3_f32 v120, v120, v88, v89
	v_max3_f32 v120, v120, v90, v91
	v_max3_f32 v120, v120, v92, v93
	v_max3_f32 v120, v120, v94, v95
	v_max3_f32 v120, v120, v64, v65
	v_max3_f32 v120, v120, v66, v67
	v_max3_f32 v120, v120, v68, v69
	v_max3_f32 v120, v120, v70, v71
	v_max3_f32 v120, v120, v72, v73
	v_max3_f32 v120, v120, v74, v75
	v_max3_f32 v120, v120, v76, v77
	v_max3_f32 v120, v120, v78, v79
	s_cbranch_scc0 .Lmx2_first
	v_cmp_ge_f32_e32 vcc, s62, v120
	s_cmp_lg_u64 vcc, exec
	s_mov_b64 s[34:35], 0
	s_mov_b64 s[30:31], 0
	s_cbranch_scc1 .Lmx2_slow
	s_branch .LBB0_164

.LBB0_164:
	v_exp_f32_e32 v80, v80
	v_exp_f32_e32 v81, v81
	v_exp_f32_e32 v82, v82
	v_exp_f32_e32 v83, v83
	v_exp_f32_e32 v84, v84
	v_exp_f32_e32 v120, v64
	v_exp_f32_e32 v85, v85
	v_add_f32_e32 v64, v81, v80
	v_exp_f32_e32 v86, v86
	v_add_f32_e32 v64, v82, v64
	v_exp_f32_e32 v87, v87
	v_add_f32_e32 v64, v83, v64
	v_exp_f32_e32 v88, v88
	v_add_f32_e32 v64, v84, v64
	v_exp_f32_e32 v89, v89
	v_add_f32_e32 v64, v85, v64
	v_exp_f32_e32 v90, v90
	v_add_f32_e32 v64, v86, v64
	v_exp_f32_e32 v91, v91
	v_add_f32_e32 v64, v87, v64
	v_exp_f32_e32 v92, v92
	v_add_f32_e32 v64, v88, v64
	v_exp_f32_e32 v93, v93
	v_add_f32_e32 v64, v89, v64
	v_exp_f32_e32 v94, v94
	v_add_f32_e32 v64, v90, v64
	v_exp_f32_e32 v95, v95
	v_add_f32_e32 v64, v91, v64
	v_add_f32_e32 v64, v92, v64
	v_exp_f32_e32 v65, v65
	v_add_f32_e32 v64, v93, v64
	v_exp_f32_e32 v133, v66
	v_add_f32_e32 v64, v94, v64
	v_exp_f32_e32 v134, v67
	v_add_f32_e32 v64, v95, v64
	v_exp_f32_e32 v135, v68
	v_add_f32_e32 v64, v120, v64
	v_exp_f32_e32 v136, v69
	v_add_f32_e32 v64, v65, v64
	v_exp_f32_e32 v137, v70
	v_add_f32_e32 v64, v133, v64
	v_exp_f32_e32 v138, v71
	v_add_f32_e32 v64, v134, v64
	v_exp_f32_e32 v139, v72
	v_add_f32_e32 v64, v135, v64
	v_exp_f32_e32 v140, v73
	v_add_f32_e32 v64, v136, v64
	v_exp_f32_e32 v141, v74
	v_add_f32_e32 v64, v137, v64
	v_exp_f32_e32 v142, v75
	v_add_f32_e32 v64, v138, v64
	v_exp_f32_e32 v143, v76
	v_add_f32_e32 v64, v139, v64
	v_exp_f32_e32 v146, v77
	v_add_f32_e32 v64, v140, v64
	v_exp_f32_e32 v147, v78
	v_add_f32_e32 v64, v141, v64
	v_exp_f32_e32 v148, v79
	v_add_f32_e32 v64, v142, v64
	v_add_f32_e32 v64, v143, v64
	v_add_f32_e32 v64, v146, v64
	v_add_f32_e32 v64, v147, v64
	v_add_f32_e32 v64, v148, v64
	s_add_i32 s5, s5, 1
	v_fma_f32 v131, v131, v132, v64
	v_cvt_pk_bf16_f32 v66, v80, v81
	v_cvt_pk_bf16_f32 v67, v82, v83
	v_cvt_pk_bf16_f32 v68, v84, v85
	v_cvt_pk_bf16_f32 v69, v86, v87
	v_cvt_pk_bf16_f32 v70, v88, v89
	v_cvt_pk_bf16_f32 v71, v90, v91
	v_cvt_pk_bf16_f32 v72, v92, v93
	v_cvt_pk_bf16_f32 v73, v94, v95
	v_cvt_pk_bf16_f32 v74, v120, v65
	v_cvt_pk_bf16_f32 v75, v133, v134
	v_cvt_pk_bf16_f32 v76, v135, v136
	v_cvt_pk_bf16_f32 v77, v137, v138
	v_cvt_pk_bf16_f32 v78, v139, v140
	v_cvt_pk_bf16_f32 v79, v141, v142
	v_cvt_pk_bf16_f32 v80, v143, v146
	v_cvt_pk_bf16_f32 v81, v147, v148
	s_nop 0
	v_permlane32_swap_b32_e32 v66, v68
	v_permlane32_swap_b32_e32 v67, v69
	v_permlane32_swap_b32_e32 v70, v72
	v_permlane32_swap_b32_e32 v71, v73
	v_permlane32_swap_b32_e32 v74, v76
	v_permlane32_swap_b32_e32 v75, v77
	v_permlane32_swap_b32_e32 v78, v80
	v_permlane32_swap_b32_e32 v79, v81
	ds_read_b64_tr_b16 v[82:83], v199 offset:0
	ds_read_b64_tr_b16 v[84:85], v199 offset:0x800
	ds_read_b64_tr_b16 v[86:87], v199 offset:0x1000
	ds_read_b64_tr_b16 v[88:89], v199 offset:0x1800
	ds_read_b64_tr_b16 v[90:91], v199 offset:0x2000
	ds_read_b64_tr_b16 v[92:93], v199 offset:0x2800
	ds_read_b64_tr_b16 v[132:133], v199 offset:0x3000
	ds_read_b64_tr_b16 v[134:135], v199 offset:0x3800
	ds_read_b64_tr_b16 v[136:137], v199 offset:0x200
	ds_read_b64_tr_b16 v[138:139], v199 offset:0xa00
	ds_read_b64_tr_b16 v[140:141], v199 offset:0x1200
	ds_read_b64_tr_b16 v[142:143], v199 offset:0x1a00
	ds_read_b64_tr_b16 v[146:147], v199 offset:0x2200
	ds_read_b64_tr_b16 v[148:149], v199 offset:0x2a00
	ds_read_b64_tr_b16 v[150:151], v199 offset:0x3200
	ds_read_b64_tr_b16 v[152:153], v199 offset:0x3a00
	s_waitcnt lgkmcnt(8)
	s_nop 0
	v_mfma_f32_32x32x16_bf16 v[48:63], v[66:69], v[82:85], v[48:63]
	ds_read_b64_tr_b16 v[82:83], v199 offset:0x400
	ds_read_b64_tr_b16 v[84:85], v199 offset:0xc00
	v_mfma_f32_32x32x16_bf16 v[48:63], v[70:73], v[86:89], v[48:63]
	ds_read_b64_tr_b16 v[86:87], v199 offset:0x1400
	ds_read_b64_tr_b16 v[88:89], v199 offset:0x1c00
	v_mfma_f32_32x32x16_bf16 v[48:63], v[74:77], v[90:93], v[48:63]
	ds_read_b64_tr_b16 v[90:91], v199 offset:0x2400
	ds_read_b64_tr_b16 v[92:93], v199 offset:0x2c00
	v_mfma_f32_32x32x16_bf16 v[48:63], v[78:81], v[132:135], v[48:63]
	ds_read_b64_tr_b16 v[132:133], v199 offset:0x3400
	ds_read_b64_tr_b16 v[134:135], v199 offset:0x3c00
	s_waitcnt lgkmcnt(8)
	v_mfma_f32_32x32x16_bf16 v[32:47], v[66:69], v[136:139], v[32:47]
	ds_read_b64_tr_b16 v[136:137], v199 offset:0x600
	ds_read_b64_tr_b16 v[138:139], v199 offset:0xe00
	v_mfma_f32_32x32x16_bf16 v[32:47], v[70:73], v[140:143], v[32:47]
	ds_read_b64_tr_b16 v[140:141], v199 offset:0x1600
	ds_read_b64_tr_b16 v[142:143], v199 offset:0x1e00
	v_mfma_f32_32x32x16_bf16 v[32:47], v[74:77], v[146:149], v[32:47]
	ds_read_b64_tr_b16 v[146:147], v199 offset:0x2600
	ds_read_b64_tr_b16 v[148:149], v199 offset:0x2e00
	v_mfma_f32_32x32x16_bf16 v[32:47], v[78:81], v[150:153], v[32:47]
	ds_read_b64_tr_b16 v[150:151], v199 offset:0x3600
	ds_read_b64_tr_b16 v[152:153], v199 offset:0x3e00
	s_waitcnt lgkmcnt(8)
	v_mfma_f32_32x32x16_bf16 v[16:31], v[66:69], v[82:85], v[16:31]
	s_waitcnt lgkmcnt(0)
	v_mfma_f32_32x32x16_bf16 v[16:31], v[70:73], v[86:89], v[16:31]
	v_mfma_f32_32x32x16_bf16 v[16:31], v[74:77], v[90:93], v[16:31]
	v_mfma_f32_32x32x16_bf16 v[16:31], v[78:81], v[132:135], v[16:31]
	v_mfma_f32_32x32x16_bf16 v[0:15], v[66:69], v[136:139], v[0:15]
	s_waitcnt vmcnt(0)
	s_add_i32 s67, s67, 0x8000
	s_cmp_eq_u32 s5, 32
	s_waitcnt vmcnt(0) lgkmcnt(0)
	s_barrier
	ds_read_b128 v[132:135], v217 offset:0
	ds_read_b128 v[136:139], v217 offset:0x1000
	ds_read_b128 v[202:205], v210 offset:0
	ds_read_b128 v[206:209], v210 offset:0x1000
	s_cmp_eq_u32 s5, 32
	v_mfma_f32_32x32x16_bf16 v[0:15], v[70:73], v[140:143], v[0:15]
	v_mfma_f32_32x32x16_bf16 v[0:15], v[74:77], v[146:149], v[0:15]
	v_mfma_f32_32x32x16_bf16 v[0:15], v[78:81], v[150:153], v[0:15]
	s_cbranch_scc1 .LBB0_166
	s_and_b32 s53, s5, 1
	s_cmp_eq_u32 s5, 31
	s_movk_i32 s0, 0x2000
	s_cbranch_scc0 .LBB0_151
	s_branch .LBB0_152
